# a9 + attention E-wave loop-top address math and global loads issued inside the QK MFMA burst
# baseline (speedup 1.0000x reference)
.LBB0_633:
	s_setprio 1
	s_waitcnt vmcnt(5) lgkmcnt(11)
	v_mfma_f32_32x32x16_bf16 v[32:47], v[32:35], v[84:87], 0
	v_add_f32_e32 v220, v163, v159
	v_add_f32_e32 v220, v204, v220
	v_add_f32_e32 v220, v173, v220
	s_waitcnt lgkmcnt(9)
	v_mfma_f32_32x32x16_bf16 v[48:63], v[128:131], v[84:87], 0
	s_add_i32 s22, s8, s41
	s_and_b32 s22, s22, 0x7f
	s_mulk_i32 s22, 0x3000
	v_lshl_add_u64 v[222:223], v[154:155], 0, s[22:23]
	v_add_f32_e32 v220, v205, v220
	v_add_f32_e32 v220, v190, v220
	s_waitcnt vmcnt(4)
	v_mfma_f32_32x32x16_bf16 v[32:47], v[116:119], v[80:83], v[32:47]
	v_add_co_u32_e32 v226, vcc, s54, v222
	s_and_b32 s22, s9, 0xfe000
	s_nop 0
	v_addc_co_u32_e32 v227, vcc, 0, v223, vcc
	v_lshl_add_u64 v[224:225], v[152:153], 0, s[22:23]
	v_add_f32_e32 v220, v206, v220
	s_waitcnt lgkmcnt(8)
	v_mfma_f32_32x32x16_bf16 v[48:63], v[124:127], v[80:83], v[48:63]
	global_load_dwordx4 v[140:143], v[222:223], off
	global_load_dwordx4 v[144:147], v[226:227], off
	global_load_dwordx4 v[136:139], v[224:225], off
	global_load_dwordx4 v[148:151], v[226:227], off offset:-4096
	global_load_dwordx4 v[132:135], v[224:225], off offset:64
	s_mov_b32 s22, s39
	s_mov_b32 s39, s59
	s_and_b32 s44, s41, 1
	s_add_i32 s41, s41, 1
	v_add_f32_e32 v220, v191, v220
	s_waitcnt vmcnt(8) lgkmcnt(7)
	v_mfma_f32_32x32x16_bf16 v[32:47], v[112:115], v[76:79], v[32:47]
	v_add_f32_e32 v220, v207, v220
	v_add_f32_e32 v220, v192, v220
	v_add_f32_e32 v220, v208, v220
	v_add_f32_e32 v220, v193, v220
	s_waitcnt lgkmcnt(5)
	v_mfma_f32_32x32x16_bf16 v[48:63], v[108:111], v[76:79], v[48:63]
	v_add_f32_e32 v220, v209, v220
	v_add_f32_e32 v220, v194, v220
	v_add_f32_e32 v220, v210, v220
	s_waitcnt vmcnt(7)
	v_mfma_f32_32x32x16_bf16 v[32:47], v[100:103], v[72:75], v[32:47]
	v_add_f32_e32 v220, v195, v220
	v_add_f32_e32 v220, v211, v220
	v_add_f32_e32 v220, v196, v220
	s_waitcnt lgkmcnt(4)
	v_mfma_f32_32x32x16_bf16 v[48:63], v[104:107], v[72:75], v[48:63]
	v_add_f32_e32 v220, v212, v220
	v_add_f32_e32 v220, v197, v220
	v_add_f32_e32 v220, v213, v220
	s_waitcnt vmcnt(6) lgkmcnt(3)
	v_mfma_f32_32x32x16_bf16 v[32:47], v[92:95], v[68:71], v[32:47]
	v_add_f32_e32 v220, v198, v220
	v_add_f32_e32 v220, v214, v220
	v_add_f32_e32 v220, v199, v220
	s_waitcnt lgkmcnt(1)
	v_mfma_f32_32x32x16_bf16 v[48:63], v[120:123], v[68:71], v[48:63]
	v_add_f32_e32 v220, v215, v220
	v_add_f32_e32 v220, v200, v220
	v_add_f32_e32 v220, v216, v220
	s_waitcnt vmcnt(5)
	v_mfma_f32_32x32x16_bf16 v[32:47], v[88:91], v[64:67], v[32:47]
	v_add_f32_e32 v220, v201, v220
	v_add_f32_e32 v220, v217, v220
	v_add_f32_e32 v220, v202, v220
	s_waitcnt lgkmcnt(0)
	v_mfma_f32_32x32x16_bf16 v[48:63], v[96:99], v[64:67], v[48:63]
	v_add_f32_e32 v220, v218, v220
	v_add_f32_e32 v220, v203, v220
	v_add_f32_e32 v159, v219, v220
	s_setprio 0
	s_mul_i32 s43, s44, 0x2400
	v_add_u32_e32 v100, s43, v157
	ds_read_b128 v[88:91], v100 offset:39936
	ds_read_b128 v[96:99], v100 offset:39968
	ds_read_b128 v[92:95], v100 offset:44544
	ds_read_b128 v[164:167], v100 offset:44576
	ds_read_b128 v[174:177], v100 offset:40000
	ds_read_b128 v[178:181], v100 offset:40032
	ds_read_b128 v[182:185], v100 offset:44608
	ds_read_b128 v[186:189], v100 offset:44640
	v_exp_f32_e32 v163, v32
	v_exp_f32_e32 v173, v33
	v_exp_f32_e32 v190, v34
	v_exp_f32_e32 v191, v35
	v_exp_f32_e32 v192, v36
	v_exp_f32_e32 v193, v37
	v_exp_f32_e32 v194, v38
	v_exp_f32_e32 v195, v39
	v_cvt_pk_bf16_f32 v36, v163, v173
	v_cvt_pk_bf16_f32 v37, v190, v191
	v_cvt_pk_bf16_f32 v38, v192, v193
	v_cvt_pk_bf16_f32 v39, v194, v195
	v_exp_f32_e32 v196, v40
	v_exp_f32_e32 v197, v41
	s_waitcnt lgkmcnt(7)
	v_mfma_f32_32x32x16_bf16 v[16:31], v[88:91], v[36:39], v[16:31]
	v_exp_f32_e32 v198, v42
	v_exp_f32_e32 v199, v43
	v_exp_f32_e32 v200, v44
	v_exp_f32_e32 v201, v45
	v_exp_f32_e32 v202, v46
	v_exp_f32_e32 v203, v47
	v_exp_f32_e32 v204, v48
	s_waitcnt lgkmcnt(5)
	v_mfma_f32_32x32x16_bf16 v[0:15], v[92:95], v[36:39], v[0:15]
	v_exp_f32_e32 v205, v49
	s_mul_i32 s43, s22, 0x3400
	v_add_u32_e32 v40, s43, v158
	v_cvt_pk_bf16_f32 v36, v196, v197
	v_cvt_pk_bf16_f32 v37, v198, v199
	v_cvt_pk_bf16_f32 v38, v200, v201
	v_cvt_pk_bf16_f32 v39, v202, v203
	v_exp_f32_e32 v206, v50
	ds_read_b128 v[32:35], v40
	ds_read_b128 v[116:119], v40 offset:32
	ds_read_b128 v[128:131], v40 offset:6656
	ds_read_b128 v[124:127], v40 offset:6688
	ds_read_b128 v[108:111], v40 offset:6720
	ds_read_b128 v[112:115], v40 offset:64
	ds_read_b128 v[100:103], v40 offset:96
	ds_read_b128 v[104:107], v40 offset:6752
	ds_read_b128 v[92:95], v40 offset:128
	ds_read_b128 v[88:91], v40 offset:160
	v_mfma_f32_32x32x16_bf16 v[16:31], v[96:99], v[36:39], v[16:31]
	ds_read_b128 v[120:123], v40 offset:6784
	ds_read_b128 v[96:99], v40 offset:6816
	v_cvt_pk_bf16_f32 v40, v204, v205
	v_exp_f32_e32 v207, v51
	s_waitcnt lgkmcnt(14)
	v_mfma_f32_32x32x16_bf16 v[0:15], v[164:167], v[36:39], v[0:15]
	v_exp_f32_e32 v208, v52
	v_exp_f32_e32 v209, v53
	v_exp_f32_e32 v210, v54
	v_exp_f32_e32 v211, v55
	v_cvt_pk_bf16_f32 v41, v206, v207
	v_cvt_pk_bf16_f32 v42, v208, v209
	v_cvt_pk_bf16_f32 v43, v210, v211
	v_exp_f32_e32 v212, v56
	v_exp_f32_e32 v213, v57
	v_mfma_f32_32x32x16_bf16 v[16:31], v[174:177], v[40:43], v[16:31]
	v_exp_f32_e32 v214, v58
	v_exp_f32_e32 v215, v59
	v_exp_f32_e32 v216, v60
	v_exp_f32_e32 v217, v61
	v_exp_f32_e32 v218, v62
	v_exp_f32_e32 v219, v63
	s_waitcnt lgkmcnt(13)
	v_mfma_f32_32x32x16_bf16 v[0:15], v[182:185], v[40:43], v[0:15]
	v_cvt_pk_bf16_f32 v36, v212, v213
	v_cvt_pk_bf16_f32 v37, v214, v215
	v_cvt_pk_bf16_f32 v38, v216, v217
	v_cvt_pk_bf16_f32 v39, v218, v219
	s_nop 1
	v_mfma_f32_32x32x16_bf16 v[16:31], v[178:181], v[36:39], v[16:31]
	s_waitcnt lgkmcnt(12)
	v_mfma_f32_32x32x16_bf16 v[0:15], v[186:189], v[36:39], v[0:15]
	s_mul_i32 s43, s59, 0x3400
	s_xor_b32 s44, s44, 1
	s_addk_i32 s9, 0x2000
	s_mov_b32 s59, s42
	s_mov_b32 s42, s22
	s_add_i32 s22, s43, 0
	s_mulk_i32 s44, 0x2400
	v_add_u32_e32 v38, s22, v160
	s_cmpk_lg_i32 s41, 0x7e
	v_add_u32_e32 v36, s22, v162
	v_add_u32_e32 v37, s22, v161
	v_add_u32_e32 v39, s44, v156
	s_waitcnt vmcnt(4)
	ds_write_b128 v38, v[140:143]
	s_waitcnt vmcnt(1)
	ds_write_b128 v37, v[148:151]
	ds_write_b128 v36, v[144:147]
	ds_write_b16 v39, v136 offset:39936
	ds_write_b16_d16_hi v39, v136 offset:40080
	ds_write_b16 v39, v137 offset:40224
	ds_write_b16_d16_hi v39, v137 offset:40368
	ds_write_b16 v39, v138 offset:40512
	ds_write_b16_d16_hi v39, v138 offset:40656
	ds_write_b16 v39, v139 offset:40800
	ds_write_b16_d16_hi v39, v139 offset:40944
	s_waitcnt vmcnt(0)
	ds_write_b16 v39, v132 offset:44544
	ds_write_b16_d16_hi v39, v132 offset:44688
	ds_write_b16 v39, v133 offset:44832
	ds_write_b16_d16_hi v39, v133 offset:44976
	ds_write_b16 v39, v134 offset:45120
	ds_write_b16_d16_hi v39, v134 offset:45264
	ds_write_b16 v39, v135 offset:45408
	ds_write_b16_d16_hi v39, v135 offset:45552
	s_waitcnt lgkmcnt(0)
	s_barrier
	s_cbranch_scc1 .LBB0_633
	s_add_i32 s8, s40, 0xfe000
	s_and_b32 s22, s8, 0xfe000
	v_lshl_add_u64 v[36:37], v[152:153], 0, s[22:23]
	global_load_dwordx4 v[132:135], v[36:37], off
	global_load_dwordx4 v[136:139], v[36:37], off offset:64
	s_setprio 1
	v_mfma_f32_32x32x16_bf16 v[48:63], v[32:35], v[84:87], 0
	v_add_f32_e32 v220, v163, v159
	v_add_f32_e32 v220, v204, v220
	v_add_f32_e32 v220, v173, v220
	v_mfma_f32_32x32x16_bf16 v[32:47], v[128:131], v[84:87], 0
	v_add_f32_e32 v220, v205, v220
	v_add_f32_e32 v220, v190, v220
	v_add_f32_e32 v220, v206, v220
	v_mfma_f32_32x32x16_bf16 v[32:47], v[124:127], v[80:83], v[32:47]
	v_add_f32_e32 v220, v191, v220
	v_add_f32_e32 v220, v207, v220
	v_add_f32_e32 v220, v192, v220
	v_mfma_f32_32x32x16_bf16 v[48:63], v[116:119], v[80:83], v[48:63]
	v_add_f32_e32 v220, v208, v220
	v_add_f32_e32 v220, v193, v220
	v_add_f32_e32 v220, v209, v220
	v_mfma_f32_32x32x16_bf16 v[32:47], v[108:111], v[76:79], v[32:47]
	v_add_f32_e32 v220, v194, v220
	v_add_f32_e32 v220, v210, v220
	v_add_f32_e32 v220, v195, v220
	v_mfma_f32_32x32x16_bf16 v[48:63], v[112:115], v[76:79], v[48:63]
	v_add_f32_e32 v220, v211, v220
	v_add_f32_e32 v220, v196, v220
	v_add_f32_e32 v220, v212, v220
	v_mfma_f32_32x32x16_bf16 v[32:47], v[104:107], v[72:75], v[32:47]
	v_add_f32_e32 v220, v197, v220
	v_add_f32_e32 v220, v213, v220
	v_add_f32_e32 v220, v198, v220
	v_mfma_f32_32x32x16_bf16 v[48:63], v[100:103], v[72:75], v[48:63]
	v_add_f32_e32 v220, v214, v220
	v_add_f32_e32 v220, v199, v220
	v_add_f32_e32 v220, v215, v220
	v_mfma_f32_32x32x16_bf16 v[32:47], v[120:123], v[68:71], v[32:47]
	v_add_f32_e32 v220, v200, v220
	v_add_f32_e32 v220, v216, v220
	v_mfma_f32_32x32x16_bf16 v[48:63], v[92:95], v[68:71], v[48:63]
	v_add_f32_e32 v220, v201, v220
	v_add_f32_e32 v220, v217, v220
	v_mfma_f32_32x32x16_bf16 v[32:47], v[96:99], v[64:67], v[32:47]
	v_add_f32_e32 v220, v202, v220
	v_add_f32_e32 v220, v218, v220
	v_mfma_f32_32x32x16_bf16 v[48:63], v[88:91], v[64:67], v[48:63]
	v_add_f32_e32 v220, v203, v220
	v_add_f32_e32 v159, v219, v220
	s_setprio 0
	ds_read_b128 v[88:91], v157 offset:39936
	ds_read_b128 v[92:95], v157 offset:39968
	ds_read_b128 v[96:99], v157 offset:44544
	ds_read_b128 v[100:103], v157 offset:44576
	ds_read_b128 v[104:107], v157 offset:40000
	ds_read_b128 v[108:111], v157 offset:40032
	ds_read_b128 v[112:115], v157 offset:44608
	ds_read_b128 v[116:119], v157 offset:44640
	s_nop 2
	v_exp_f32_e32 v140, v48
	v_exp_f32_e32 v141, v49
	v_exp_f32_e32 v142, v50
	v_exp_f32_e32 v143, v51
	v_exp_f32_e32 v52, v52
	v_exp_f32_e32 v53, v53
	v_exp_f32_e32 v54, v54
	v_exp_f32_e32 v55, v55
	v_cvt_pk_bf16_f32 v48, v140, v141
	v_cvt_pk_bf16_f32 v49, v142, v143
	v_cvt_pk_bf16_f32 v50, v52, v53
	v_cvt_pk_bf16_f32 v51, v54, v55
	v_exp_f32_e32 v56, v56
	v_exp_f32_e32 v57, v57
	s_waitcnt lgkmcnt(7)
	v_mfma_f32_32x32x16_bf16 v[16:31], v[88:91], v[48:51], v[16:31]
	v_exp_f32_e32 v58, v58
	v_exp_f32_e32 v59, v59
	v_exp_f32_e32 v60, v60
	v_exp_f32_e32 v61, v61
	v_exp_f32_e32 v62, v62
	v_exp_f32_e32 v63, v63
	v_exp_f32_e32 v144, v32
	s_waitcnt lgkmcnt(5)
	v_mfma_f32_32x32x16_bf16 v[0:15], v[96:99], v[48:51], v[0:15]
	v_cvt_pk_bf16_f32 v48, v56, v57
	v_cvt_pk_bf16_f32 v49, v58, v59
	v_cvt_pk_bf16_f32 v50, v60, v61
	v_cvt_pk_bf16_f32 v51, v62, v63
	v_exp_f32_e32 v145, v33
	v_exp_f32_e32 v146, v34
	v_exp_f32_e32 v147, v35
	v_mfma_f32_32x32x16_bf16 v[16:31], v[92:95], v[48:51], v[16:31]
	v_exp_f32_e32 v148, v36
	v_cvt_pk_bf16_f32 v32, v144, v145
	v_cvt_pk_bf16_f32 v33, v146, v147
	v_exp_f32_e32 v149, v41
	v_exp_f32_e32 v150, v42
	v_exp_f32_e32 v151, v43
	v_exp_f32_e32 v44, v44
	s_waitcnt lgkmcnt(4)
	v_mfma_f32_32x32x16_bf16 v[0:15], v[100:103], v[48:51], v[0:15]
	v_exp_f32_e32 v48, v37
	v_exp_f32_e32 v49, v38
	v_exp_f32_e32 v50, v39
	v_exp_f32_e32 v51, v40
	v_cvt_pk_bf16_f32 v34, v148, v48
	v_exp_f32_e32 v45, v45
	v_cvt_pk_bf16_f32 v35, v49, v50
	v_exp_f32_e32 v46, v46
	v_exp_f32_e32 v47, v47
	s_waitcnt lgkmcnt(3)
	v_mfma_f32_32x32x16_bf16 v[16:31], v[104:107], v[32:35], v[16:31]
	v_add_u32_e32 v128, s43, v158
	s_waitcnt lgkmcnt(1)
	v_mfma_f32_32x32x16_bf16 v[0:15], v[112:115], v[32:35], v[0:15]
	v_cvt_pk_bf16_f32 v32, v51, v149
	v_cvt_pk_bf16_f32 v33, v150, v151
	v_cvt_pk_bf16_f32 v34, v44, v45
	v_cvt_pk_bf16_f32 v35, v46, v47
	s_nop 1
	v_mfma_f32_32x32x16_bf16 v[16:31], v[108:111], v[32:35], v[16:31]
	ds_read_b128 v[36:39], v128
	ds_read_b128 v[88:91], v128 offset:32
	ds_read_b128 v[40:43], v128 offset:6656
	ds_read_b128 v[92:95], v128 offset:6688
	ds_read_b128 v[96:99], v128 offset:64
	ds_read_b128 v[100:103], v128 offset:96
	ds_read_b128 v[104:107], v128 offset:6720
	ds_read_b128 v[108:111], v128 offset:6752
	ds_read_b128 v[112:115], v128 offset:128
	ds_read_b128 v[120:123], v128 offset:160
	ds_read_b128 v[124:127], v128 offset:6784
	ds_read_b128 v[128:131], v128 offset:6816
	s_waitcnt lgkmcnt(12)
	v_mfma_f32_32x32x16_bf16 v[0:15], v[116:119], v[32:35], v[0:15]
	v_add_f32_e32 v32, v159, v140
	v_add_f32_e32 v32, v144, v32
	v_add_f32_e32 v32, v141, v32
	v_add_f32_e32 v32, v145, v32
	v_add_f32_e32 v32, v142, v32
	v_add_f32_e32 v32, v146, v32
	v_add_f32_e32 v32, v143, v32
	v_add_f32_e32 v32, v147, v32
	v_add_f32_e32 v32, v52, v32
	v_add_f32_e32 v32, v148, v32
	v_add_f32_e32 v32, v53, v32
	v_add_f32_e32 v32, v48, v32
	v_add_f32_e32 v32, v54, v32
	v_add_f32_e32 v32, v49, v32
	v_add_f32_e32 v32, v55, v32
	v_add_f32_e32 v32, v50, v32
	v_add_f32_e32 v32, v56, v32
	v_add_f32_e32 v32, v51, v32
	v_add_f32_e32 v32, v57, v32
	v_add_f32_e32 v32, v149, v32
	v_add_f32_e32 v32, v58, v32
	v_add_f32_e32 v32, v150, v32
	v_add_f32_e32 v32, v59, v32
	v_add_f32_e32 v32, v151, v32
	v_add_f32_e32 v32, v60, v32
	v_add_f32_e32 v32, v44, v32
	v_add_f32_e32 v32, v61, v32
	v_add_f32_e32 v32, v45, v32
	v_add_f32_e32 v32, v62, v32
	v_add_f32_e32 v32, v46, v32
	v_add_f32_e32 v32, v63, v32
	v_add_f32_e32 v116, v47, v32
	s_waitcnt vmcnt(1)
	ds_write_b16 v156, v132 offset:49152
	ds_write_b16_d16_hi v156, v132 offset:49296
	ds_write_b16 v156, v133 offset:49440
	ds_write_b16_d16_hi v156, v133 offset:49584
	ds_write_b16 v156, v134 offset:49728
	ds_write_b16_d16_hi v156, v134 offset:49872
	ds_write_b16 v156, v135 offset:50016
	ds_write_b16_d16_hi v156, v135 offset:50160
	s_waitcnt vmcnt(0)
	ds_write_b16 v156, v136 offset:53760
	ds_write_b16_d16_hi v156, v136 offset:53904
	ds_write_b16 v156, v137 offset:54048
	ds_write_b16_d16_hi v156, v137 offset:54192
	ds_write_b16 v156, v138 offset:54336
	ds_write_b16_d16_hi v156, v138 offset:54480
	ds_write_b16 v156, v139 offset:54624
	ds_write_b16_d16_hi v156, v139 offset:54768
	s_waitcnt lgkmcnt(0)
	s_barrier
	s_setprio 1
	v_mfma_f32_32x32x16_bf16 v[48:63], v[36:39], v[84:87], 0
	v_mfma_f32_32x32x16_bf16 v[32:47], v[40:43], v[84:87], 0
	v_mfma_f32_32x32x16_bf16 v[32:47], v[92:95], v[80:83], v[32:47]
	v_mfma_f32_32x32x16_bf16 v[48:63], v[88:91], v[80:83], v[48:63]
	v_mfma_f32_32x32x16_bf16 v[32:47], v[104:107], v[76:79], v[32:47]
	v_mfma_f32_32x32x16_bf16 v[48:63], v[96:99], v[76:79], v[48:63]
	v_mfma_f32_32x32x16_bf16 v[32:47], v[108:111], v[72:75], v[32:47]
	v_mfma_f32_32x32x16_bf16 v[48:63], v[100:103], v[72:75], v[48:63]
	v_mfma_f32_32x32x16_bf16 v[32:47], v[124:127], v[68:71], v[32:47]
	v_mfma_f32_32x32x16_bf16 v[48:63], v[112:115], v[68:71], v[48:63]
	v_mfma_f32_32x32x16_bf16 v[32:47], v[128:131], v[64:67], v[32:47]
	v_mfma_f32_32x32x16_bf16 v[48:63], v[120:123], v[64:67], v[48:63]
	s_setprio 0
	ds_read_b128 v[64:67], v157 offset:49152
	ds_read_b128 v[68:71], v157 offset:49184
	ds_read_b128 v[72:75], v157 offset:53760
	ds_read_b128 v[76:79], v157 offset:53792
	ds_read_b128 v[80:83], v157 offset:49216
	ds_read_b128 v[84:87], v157 offset:49248
	ds_read_b128 v[88:91], v157 offset:53824
	ds_read_b128 v[92:95], v157 offset:53856
	s_nop 2
	v_exp_f32_e32 v96, v48
	v_exp_f32_e32 v97, v49
	v_exp_f32_e32 v98, v50
	v_exp_f32_e32 v99, v51
	v_exp_f32_e32 v52, v52
	v_exp_f32_e32 v53, v53
	v_exp_f32_e32 v54, v54
	v_exp_f32_e32 v55, v55
	v_cvt_pk_bf16_f32 v48, v96, v97
	v_cvt_pk_bf16_f32 v49, v98, v99
	v_cvt_pk_bf16_f32 v50, v52, v53
	v_cvt_pk_bf16_f32 v51, v54, v55
	v_exp_f32_e32 v56, v56
	v_exp_f32_e32 v57, v57
	s_waitcnt lgkmcnt(7)
	v_mfma_f32_32x32x16_bf16 v[16:31], v[64:67], v[48:51], v[16:31]
	v_exp_f32_e32 v58, v58
	v_exp_f32_e32 v59, v59
	v_exp_f32_e32 v60, v60
	v_exp_f32_e32 v61, v61
	v_exp_f32_e32 v62, v62
	v_exp_f32_e32 v63, v63
	v_exp_f32_e32 v64, v32
	s_waitcnt lgkmcnt(5)
	v_mfma_f32_32x32x16_bf16 v[0:15], v[72:75], v[48:51], v[0:15]
	v_cvt_pk_bf16_f32 v48, v56, v57
	v_cvt_pk_bf16_f32 v49, v58, v59
	v_cvt_pk_bf16_f32 v50, v60, v61
	v_cvt_pk_bf16_f32 v51, v62, v63
	v_exp_f32_e32 v65, v33
	v_exp_f32_e32 v66, v34
	v_exp_f32_e32 v67, v35
	v_mfma_f32_32x32x16_bf16 v[16:31], v[68:71], v[48:51], v[16:31]
	v_exp_f32_e32 v36, v36
	v_exp_f32_e32 v37, v37
	v_exp_f32_e32 v38, v38
	v_exp_f32_e32 v39, v39
	v_cvt_pk_bf16_f32 v32, v64, v65
	v_cvt_pk_bf16_f32 v33, v66, v67
	v_cvt_pk_bf16_f32 v34, v36, v37
	s_waitcnt lgkmcnt(4)
	v_mfma_f32_32x32x16_bf16 v[0:15], v[76:79], v[48:51], v[0:15]
	v_cvt_pk_bf16_f32 v35, v38, v39
	v_add_f32_e32 v48, v116, v96
	v_add_f32_e32 v48, v64, v48
	v_exp_f32_e32 v40, v40
	v_exp_f32_e32 v41, v41
	v_exp_f32_e32 v42, v42
	v_exp_f32_e32 v43, v43
	s_waitcnt lgkmcnt(3)
	v_mfma_f32_32x32x16_bf16 v[16:31], v[80:83], v[32:35], v[16:31]
	v_exp_f32_e32 v44, v44
	v_exp_f32_e32 v45, v45
	v_exp_f32_e32 v46, v46
	v_exp_f32_e32 v47, v47
	v_add_f32_e32 v48, v97, v48
	v_add_f32_e32 v48, v65, v48
	v_add_f32_e32 v48, v98, v48
	s_waitcnt lgkmcnt(1)
	v_mfma_f32_32x32x16_bf16 v[0:15], v[88:91], v[32:35], v[0:15]
	v_add_f32_e32 v48, v66, v48
	v_cvt_pk_bf16_f32 v32, v40, v41
	v_cvt_pk_bf16_f32 v33, v42, v43
	v_cvt_pk_bf16_f32 v34, v44, v45
	v_cvt_pk_bf16_f32 v35, v46, v47
	v_add_f32_e32 v48, v99, v48
	s_waitcnt lgkmcnt(0)
	v_mfma_f32_32x32x16_bf16 v[16:31], v[84:87], v[32:35], v[16:31]
	s_barrier
	v_mfma_f32_32x32x16_bf16 v[0:15], v[92:95], v[32:35], v[0:15]
	v_add_f32_e32 v32, v67, v48
	v_add_f32_e32 v32, v52, v32
	v_add_f32_e32 v32, v36, v32
	v_add_f32_e32 v32, v53, v32
	v_add_f32_e32 v32, v37, v32
	v_add_f32_e32 v32, v54, v32
	v_add_f32_e32 v32, v38, v32
	v_add_f32_e32 v32, v55, v32
	v_add_f32_e32 v32, v39, v32
	v_add_f32_e32 v32, v56, v32
	v_add_f32_e32 v32, v40, v32
	v_add_f32_e32 v32, v57, v32
	v_add_f32_e32 v32, v41, v32
	v_add_f32_e32 v32, v58, v32
	v_add_f32_e32 v32, v42, v32
	v_add_f32_e32 v32, v59, v32
	v_add_f32_e32 v32, v43, v32
	v_add_f32_e32 v32, v60, v32
	v_add_f32_e32 v32, v44, v32
	v_add_f32_e32 v32, v61, v32
	v_add_f32_e32 v32, v45, v32
	v_add_f32_e32 v32, v62, v32
	v_add_f32_e32 v32, v46, v32
	v_add_f32_e32 v32, v63, v32
	v_add_f32_e32 v32, v47, v32
	v_mov_b32_e32 v33, v32
	s_nop 1
	v_permlane32_swap_b32_e32 v32, v33
	s_branch .LBB0_592
